# best (waits+prio+rotation) + 64-byte alignment of the 9 hot loop heads (2 attention tile loops, 7 GEMM K-loops)
# speedup vs baseline: 1.0050x; 1.0050x over previous
.LBB0_265:
	s_ashr_i32 s49, s48, 31
	s_lshl_b64 s[12:13], s[48:49], 20
	s_add_u32 s52, s66, s12
	s_addc_u32 s53, s67, s13
	s_and_b64 s[12:13], s[6:7], exec
	s_cselect_b32 s11, s53, s9
	s_cselect_b32 s12, s52, s8
	s_ashr_i32 s45, s44, 31
	s_lshl_b64 s[58:59], s[44:45], 20
	s_add_u32 s58, s69, s58
	s_addc_u32 s59, s76, s59
	s_and_b64 s[64:65], s[6:7], exec
	s_cselect_b32 s13, s59, s63
	s_cselect_b32 s45, s58, s62
	s_add_u32 s8, s8, 0x80080
	s_addc_u32 s9, s9, 0
	s_add_u32 s49, s62, 0x100
	v_mov_b32_e32 v2, 0
	s_addc_u32 s61, s63, 0
	s_mov_b32 s74, -2
	s_waitcnt lgkmcnt(0)
	v_mov_b32_e32 v3, v2
	v_mov_b32_e32 v4, v2
	v_mov_b32_e32 v5, v2
	v_mov_b32_e32 v6, v2
	v_mov_b32_e32 v7, v2
	v_mov_b32_e32 v8, v2
	v_mov_b32_e32 v9, v2
	v_mov_b32_e32 v18, v2
	v_mov_b32_e32 v19, v2
	v_mov_b32_e32 v20, v2
	v_mov_b32_e32 v21, v2
	v_mov_b32_e32 v22, v2
	v_mov_b32_e32 v23, v2
	v_mov_b32_e32 v24, v2
	v_mov_b32_e32 v25, v2
	v_mov_b32_e32 v34, v2
	v_mov_b32_e32 v35, v2
	v_mov_b32_e32 v36, v2
	v_mov_b32_e32 v37, v2
	v_mov_b32_e32 v38, v2
	v_mov_b32_e32 v39, v2
	v_mov_b32_e32 v40, v2
	v_mov_b32_e32 v41, v2
	v_mov_b32_e32 v50, v2
	v_mov_b32_e32 v51, v2
	v_mov_b32_e32 v52, v2
	v_mov_b32_e32 v53, v2
	v_mov_b32_e32 v54, v2
	v_mov_b32_e32 v55, v2
	v_mov_b32_e32 v56, v2
	v_mov_b32_e32 v57, v2
	v_mov_b32_e32 v10, v2
	v_mov_b32_e32 v11, v2
	v_mov_b32_e32 v12, v2
	v_mov_b32_e32 v13, v2
	v_mov_b32_e32 v14, v2
	v_mov_b32_e32 v15, v2
	v_mov_b32_e32 v16, v2
	v_mov_b32_e32 v17, v2
	v_mov_b32_e32 v26, v2
	v_mov_b32_e32 v27, v2
	v_mov_b32_e32 v28, v2
	v_mov_b32_e32 v29, v2
	v_mov_b32_e32 v30, v2
	v_mov_b32_e32 v31, v2
	v_mov_b32_e32 v32, v2
	v_mov_b32_e32 v33, v2
	v_mov_b32_e32 v42, v2
	v_mov_b32_e32 v43, v2
	v_mov_b32_e32 v44, v2
	v_mov_b32_e32 v45, v2
	v_mov_b32_e32 v46, v2
	v_mov_b32_e32 v47, v2
	v_mov_b32_e32 v48, v2
	v_mov_b32_e32 v49, v2
	v_mov_b32_e32 v58, v2
	v_mov_b32_e32 v59, v2
	v_mov_b32_e32 v60, v2
	v_mov_b32_e32 v61, v2
	v_mov_b32_e32 v62, v2
	v_mov_b32_e32 v63, v2
	v_mov_b32_e32 v64, v2
	v_mov_b32_e32 v65, v2
	v_mov_b32_e32 v66, v2
	v_mov_b32_e32 v67, v2
	v_mov_b32_e32 v68, v2
	v_mov_b32_e32 v69, v2
	v_mov_b32_e32 v70, v2
	v_mov_b32_e32 v71, v2
	v_mov_b32_e32 v72, v2
	v_mov_b32_e32 v73, v2
	v_mov_b32_e32 v82, v2
	v_mov_b32_e32 v83, v2
	v_mov_b32_e32 v84, v2
	v_mov_b32_e32 v85, v2
	v_mov_b32_e32 v86, v2
	v_mov_b32_e32 v87, v2
	v_mov_b32_e32 v88, v2
	v_mov_b32_e32 v89, v2
	v_mov_b32_e32 v98, v2
	v_mov_b32_e32 v99, v2
	v_mov_b32_e32 v100, v2
	v_mov_b32_e32 v101, v2
	v_mov_b32_e32 v102, v2
	v_mov_b32_e32 v103, v2
	v_mov_b32_e32 v104, v2
	v_mov_b32_e32 v105, v2
	v_mov_b32_e32 v114, v2
	v_mov_b32_e32 v115, v2
	v_mov_b32_e32 v116, v2
	v_mov_b32_e32 v117, v2
	v_mov_b32_e32 v118, v2
	v_mov_b32_e32 v119, v2
	v_mov_b32_e32 v120, v2
	v_mov_b32_e32 v121, v2
	v_mov_b32_e32 v74, v2
	v_mov_b32_e32 v75, v2
	v_mov_b32_e32 v76, v2
	v_mov_b32_e32 v77, v2
	v_mov_b32_e32 v78, v2
	v_mov_b32_e32 v79, v2
	v_mov_b32_e32 v80, v2
	v_mov_b32_e32 v81, v2
	v_mov_b32_e32 v90, v2
	v_mov_b32_e32 v91, v2
	v_mov_b32_e32 v92, v2
	v_mov_b32_e32 v93, v2
	v_mov_b32_e32 v94, v2
	v_mov_b32_e32 v95, v2
	v_mov_b32_e32 v96, v2
	v_mov_b32_e32 v97, v2
	v_mov_b32_e32 v106, v2
	v_mov_b32_e32 v107, v2
	v_mov_b32_e32 v108, v2
	v_mov_b32_e32 v109, v2
	v_mov_b32_e32 v110, v2
	v_mov_b32_e32 v111, v2
	v_mov_b32_e32 v112, v2
	v_mov_b32_e32 v113, v2
	v_mov_b32_e32 v122, v2
	v_mov_b32_e32 v123, v2
	v_mov_b32_e32 v124, v2
	v_mov_b32_e32 v125, v2
	v_mov_b32_e32 v126, v2
	v_mov_b32_e32 v127, v2
	v_mov_b32_e32 v128, v2
	v_mov_b32_e32 v129, v2
	.p2align	6

.LBB0_446:
	s_ashr_i32 s39, s38, 31
	s_lshl_b64 s[12:13], s[38:39], 22
	s_add_u32 s40, s52, s12
	s_addc_u32 s41, s53, s13
	s_and_b64 s[12:13], s[2:3], exec
	s_cselect_b32 s1, s41, s7
	s_cselect_b32 s5, s40, s6
	s_ashr_i32 s25, s24, 31
	s_lshl_b64 s[12:13], s[24:25], 18
	s_add_u32 s42, s58, s12
	s_addc_u32 s43, s59, s13
	s_and_b64 s[12:13], s[2:3], exec
	s_cselect_b32 s12, s43, s45
	s_cselect_b32 s13, s42, s44
	s_add_u32 s6, s6, 0x200080
	s_addc_u32 s7, s7, 0
	s_add_u32 s25, s44, 0x100
	v_mov_b32_e32 v2, 0
	s_addc_u32 s39, s45, 0
	s_mov_b32 s74, -2
	v_mov_b32_e32 v3, v2
	v_mov_b32_e32 v4, v2
	v_mov_b32_e32 v5, v2
	v_mov_b32_e32 v6, v2
	v_mov_b32_e32 v7, v2
	v_mov_b32_e32 v8, v2
	v_mov_b32_e32 v9, v2
	v_mov_b32_e32 v18, v2
	v_mov_b32_e32 v19, v2
	v_mov_b32_e32 v20, v2
	v_mov_b32_e32 v21, v2
	v_mov_b32_e32 v22, v2
	v_mov_b32_e32 v23, v2
	v_mov_b32_e32 v24, v2
	v_mov_b32_e32 v25, v2
	v_mov_b32_e32 v34, v2
	v_mov_b32_e32 v35, v2
	v_mov_b32_e32 v36, v2
	v_mov_b32_e32 v37, v2
	v_mov_b32_e32 v38, v2
	v_mov_b32_e32 v39, v2
	v_mov_b32_e32 v40, v2
	v_mov_b32_e32 v41, v2
	v_mov_b32_e32 v50, v2
	v_mov_b32_e32 v51, v2
	v_mov_b32_e32 v52, v2
	v_mov_b32_e32 v53, v2
	v_mov_b32_e32 v54, v2
	v_mov_b32_e32 v55, v2
	v_mov_b32_e32 v56, v2
	v_mov_b32_e32 v57, v2
	v_mov_b32_e32 v10, v2
	v_mov_b32_e32 v11, v2
	v_mov_b32_e32 v12, v2
	v_mov_b32_e32 v13, v2
	v_mov_b32_e32 v14, v2
	v_mov_b32_e32 v15, v2
	v_mov_b32_e32 v16, v2
	v_mov_b32_e32 v17, v2
	v_mov_b32_e32 v26, v2
	v_mov_b32_e32 v27, v2
	v_mov_b32_e32 v28, v2
	v_mov_b32_e32 v29, v2
	v_mov_b32_e32 v30, v2
	v_mov_b32_e32 v31, v2
	v_mov_b32_e32 v32, v2
	v_mov_b32_e32 v33, v2
	v_mov_b32_e32 v42, v2
	v_mov_b32_e32 v43, v2
	v_mov_b32_e32 v44, v2
	v_mov_b32_e32 v45, v2
	v_mov_b32_e32 v46, v2
	v_mov_b32_e32 v47, v2
	v_mov_b32_e32 v48, v2
	v_mov_b32_e32 v49, v2
	v_mov_b32_e32 v58, v2
	v_mov_b32_e32 v59, v2
	v_mov_b32_e32 v60, v2
	v_mov_b32_e32 v61, v2
	v_mov_b32_e32 v62, v2
	v_mov_b32_e32 v63, v2
	v_mov_b32_e32 v64, v2
	v_mov_b32_e32 v65, v2
	v_mov_b32_e32 v66, v2
	v_mov_b32_e32 v67, v2
	v_mov_b32_e32 v68, v2
	v_mov_b32_e32 v69, v2
	v_mov_b32_e32 v70, v2
	v_mov_b32_e32 v71, v2
	v_mov_b32_e32 v72, v2
	v_mov_b32_e32 v73, v2
	v_mov_b32_e32 v82, v2
	v_mov_b32_e32 v83, v2
	v_mov_b32_e32 v84, v2
	v_mov_b32_e32 v85, v2
	v_mov_b32_e32 v86, v2
	v_mov_b32_e32 v87, v2
	v_mov_b32_e32 v88, v2
	v_mov_b32_e32 v89, v2
	v_mov_b32_e32 v98, v2
	v_mov_b32_e32 v99, v2
	v_mov_b32_e32 v100, v2
	v_mov_b32_e32 v101, v2
	v_mov_b32_e32 v102, v2
	v_mov_b32_e32 v103, v2
	v_mov_b32_e32 v104, v2
	v_mov_b32_e32 v105, v2
	v_mov_b32_e32 v114, v2
	v_mov_b32_e32 v115, v2
	v_mov_b32_e32 v116, v2
	v_mov_b32_e32 v117, v2
	v_mov_b32_e32 v118, v2
	v_mov_b32_e32 v119, v2
	v_mov_b32_e32 v120, v2
	v_mov_b32_e32 v121, v2
	v_mov_b32_e32 v74, v2
	v_mov_b32_e32 v75, v2
	v_mov_b32_e32 v76, v2
	v_mov_b32_e32 v77, v2
	v_mov_b32_e32 v78, v2
	v_mov_b32_e32 v79, v2
	v_mov_b32_e32 v80, v2
	v_mov_b32_e32 v81, v2
	v_mov_b32_e32 v90, v2
	v_mov_b32_e32 v91, v2
	v_mov_b32_e32 v92, v2
	v_mov_b32_e32 v93, v2
	v_mov_b32_e32 v94, v2
	v_mov_b32_e32 v95, v2
	v_mov_b32_e32 v96, v2
	v_mov_b32_e32 v97, v2
	v_mov_b32_e32 v106, v2
	v_mov_b32_e32 v107, v2
	v_mov_b32_e32 v108, v2
	v_mov_b32_e32 v109, v2
	v_mov_b32_e32 v110, v2
	v_mov_b32_e32 v111, v2
	v_mov_b32_e32 v112, v2
	v_mov_b32_e32 v113, v2
	v_mov_b32_e32 v122, v2
	v_mov_b32_e32 v123, v2
	v_mov_b32_e32 v124, v2
	v_mov_b32_e32 v125, v2
	v_mov_b32_e32 v126, v2
	v_mov_b32_e32 v127, v2
	v_mov_b32_e32 v128, v2
	v_mov_b32_e32 v129, v2
	.p2align	6

.LBB0_598:
	v_add_f32_e32 v184, v18, v19
	v_lshlrev_b32_e32 v18, 1, v50
	v_and_b32_e32 v18, 32, v18
	v_and_or_b32 v18, v51, s66, v18
	v_and_b32_e32 v19, 0x100, v52
	v_fmac_f32_e32 v184, 0, v56
	v_or3_b32 v187, v18, v19, v53
	s_add_i32 s35, 0, 0xc000
	v_cmp_gt_u32_e64 s[4:5], 32, v50
	v_lshl_add_u32 v186, v54, 2, s18
	v_lshlrev_b32_e32 v185, 4, v55
	v_mov_b64_e32 v[32:33], v[16:17]
	v_mov_b64_e32 v[48:49], v[16:17]
	v_mov_b64_e32 v[64:65], v[16:17]
	s_mov_b32 s96, 1
	v_add_u32_e32 v193, s35, v187
	s_lshl_b32 s97, s12, 8
	s_mov_b32 s12, 0x8000
	s_movk_i32 s74, 0x4000
	s_mov_b32 s0, 0
	v_mov_b64_e32 v[30:31], v[14:15]
	v_mov_b64_e32 v[28:29], v[12:13]
	v_mov_b64_e32 v[26:27], v[10:11]
	v_mov_b64_e32 v[24:25], v[8:9]
	v_mov_b64_e32 v[22:23], v[6:7]
	v_mov_b64_e32 v[20:21], v[4:5]
	v_mov_b64_e32 v[18:19], v[2:3]
	v_mov_b64_e32 v[46:47], v[14:15]
	v_mov_b64_e32 v[44:45], v[12:13]
	v_mov_b64_e32 v[42:43], v[10:11]
	v_mov_b64_e32 v[40:41], v[8:9]
	v_mov_b64_e32 v[38:39], v[6:7]
	v_mov_b64_e32 v[36:37], v[4:5]
	v_mov_b64_e32 v[34:35], v[2:3]
	v_mov_b64_e32 v[62:63], v[14:15]
	v_mov_b64_e32 v[60:61], v[12:13]
	v_mov_b64_e32 v[58:59], v[10:11]
	v_mov_b64_e32 v[56:57], v[8:9]
	v_mov_b64_e32 v[54:55], v[6:7]
	v_mov_b64_e32 v[52:53], v[4:5]
	v_mov_b64_e32 v[50:51], v[2:3]
	s_mov_b32 s75, s74
	s_mov_b32 s74, s0
	v_add_u32_e32 v238, s74, v193
	.p2align	6

.LBB0_665:
	v_add_f32_e32 v151, v18, v19
	v_lshlrev_b32_e32 v18, 1, v50
	v_and_b32_e32 v18, 32, v18
	v_and_or_b32 v18, v51, s67, v18
	v_and_b32_e32 v19, 0x100, v52
	v_fmac_f32_e32 v151, 0, v58
	v_or3_b32 v158, v18, v19, v53
	v_add_u32_e32 v187, v57, v56
	v_add_u32_e32 v188, 0, v56
	v_cmp_gt_u32_e64 s[4:5], 32, v50
	v_lshl_add_u32 v157, v54, 2, s18
	v_lshlrev_b32_e32 v156, 4, v55
	v_mov_b64_e32 v[32:33], v[16:17]
	v_mov_b64_e32 v[48:49], v[16:17]
	v_mov_b64_e32 v[64:65], v[16:17]
	s_mov_b32 s93, 1
	v_add_u32_e32 v185, s35, v158
	s_mov_b32 s95, 0x8000
	s_movk_i32 s94, 0x4000
	s_mov_b32 s8, 0
	v_mov_b64_e32 v[30:31], v[14:15]
	v_mov_b64_e32 v[28:29], v[12:13]
	v_mov_b64_e32 v[26:27], v[10:11]
	v_mov_b64_e32 v[24:25], v[8:9]
	v_mov_b64_e32 v[22:23], v[6:7]
	v_mov_b64_e32 v[20:21], v[4:5]
	v_mov_b64_e32 v[18:19], v[2:3]
	v_mov_b64_e32 v[46:47], v[14:15]
	v_mov_b64_e32 v[44:45], v[12:13]
	v_mov_b64_e32 v[42:43], v[10:11]
	v_mov_b64_e32 v[40:41], v[8:9]
	v_mov_b64_e32 v[38:39], v[6:7]
	v_mov_b64_e32 v[36:37], v[4:5]
	v_mov_b64_e32 v[34:35], v[2:3]
	v_mov_b64_e32 v[62:63], v[14:15]
	v_mov_b64_e32 v[60:61], v[12:13]
	v_mov_b64_e32 v[58:59], v[10:11]
	v_mov_b64_e32 v[56:57], v[8:9]
	v_mov_b64_e32 v[54:55], v[6:7]
	v_mov_b64_e32 v[52:53], v[4:5]
	v_mov_b64_e32 v[50:51], v[2:3]
	v_add_u32_e32 v189, v187, v160
	v_add_u32_e32 v190, v187, v162
	v_add_u32_e32 v191, v187, v164
	v_add_u32_e32 v192, v187, v166
	.p2align	6

.LBB0_782:
	s_ashr_i32 s25, s24, 31
	s_lshl_b64 s[38:39], s[24:25], 19
	s_add_u32 s38, s55, s38
	s_addc_u32 s39, s59, s39
	s_and_b64 s[40:41], s[2:3], exec
	s_cselect_b32 s13, s39, s45
	s_cselect_b32 s25, s38, s44
	s_ashr_i32 s23, s22, 31
	s_lshl_b64 s[40:41], s[22:23], 19
	s_add_u32 s40, s60, s40
	s_addc_u32 s41, s61, s41
	s_and_b64 s[52:53], s[2:3], exec
	s_cselect_b32 s23, s41, s49
	s_cselect_b32 s74, s40, s48
	s_add_u32 s44, s44, 0x40080
	s_addc_u32 s45, s45, 0
	s_add_u32 s75, s48, 0x100
	v_mov_b32_e32 v2, 0
	s_addc_u32 s78, s49, 0
	s_mov_b32 s79, -2
	v_mov_b32_e32 v3, v2
	v_mov_b32_e32 v4, v2
	v_mov_b32_e32 v5, v2
	v_mov_b32_e32 v6, v2
	v_mov_b32_e32 v7, v2
	v_mov_b32_e32 v8, v2
	v_mov_b32_e32 v9, v2
	v_mov_b32_e32 v18, v2
	v_mov_b32_e32 v19, v2
	v_mov_b32_e32 v20, v2
	v_mov_b32_e32 v21, v2
	v_mov_b32_e32 v22, v2
	v_mov_b32_e32 v23, v2
	v_mov_b32_e32 v24, v2
	v_mov_b32_e32 v25, v2
	v_mov_b32_e32 v34, v2
	v_mov_b32_e32 v35, v2
	v_mov_b32_e32 v36, v2
	v_mov_b32_e32 v37, v2
	v_mov_b32_e32 v38, v2
	v_mov_b32_e32 v39, v2
	v_mov_b32_e32 v40, v2
	v_mov_b32_e32 v41, v2
	v_mov_b32_e32 v50, v2
	v_mov_b32_e32 v51, v2
	v_mov_b32_e32 v52, v2
	v_mov_b32_e32 v53, v2
	v_mov_b32_e32 v54, v2
	v_mov_b32_e32 v55, v2
	v_mov_b32_e32 v56, v2
	v_mov_b32_e32 v57, v2
	v_mov_b32_e32 v10, v2
	v_mov_b32_e32 v11, v2
	v_mov_b32_e32 v12, v2
	v_mov_b32_e32 v13, v2
	v_mov_b32_e32 v14, v2
	v_mov_b32_e32 v15, v2
	v_mov_b32_e32 v16, v2
	v_mov_b32_e32 v17, v2
	v_mov_b32_e32 v26, v2
	v_mov_b32_e32 v27, v2
	v_mov_b32_e32 v28, v2
	v_mov_b32_e32 v29, v2
	v_mov_b32_e32 v30, v2
	v_mov_b32_e32 v31, v2
	v_mov_b32_e32 v32, v2
	v_mov_b32_e32 v33, v2
	v_mov_b32_e32 v42, v2
	v_mov_b32_e32 v43, v2
	v_mov_b32_e32 v44, v2
	v_mov_b32_e32 v45, v2
	v_mov_b32_e32 v46, v2
	v_mov_b32_e32 v47, v2
	v_mov_b32_e32 v48, v2
	v_mov_b32_e32 v49, v2
	v_mov_b32_e32 v58, v2
	v_mov_b32_e32 v59, v2
	v_mov_b32_e32 v60, v2
	v_mov_b32_e32 v61, v2
	v_mov_b32_e32 v62, v2
	v_mov_b32_e32 v63, v2
	v_mov_b32_e32 v64, v2
	v_mov_b32_e32 v65, v2
	v_mov_b32_e32 v66, v2
	v_mov_b32_e32 v67, v2
	v_mov_b32_e32 v68, v2
	v_mov_b32_e32 v69, v2
	v_mov_b32_e32 v70, v2
	v_mov_b32_e32 v71, v2
	v_mov_b32_e32 v72, v2
	v_mov_b32_e32 v73, v2
	v_mov_b32_e32 v82, v2
	v_mov_b32_e32 v83, v2
	v_mov_b32_e32 v84, v2
	v_mov_b32_e32 v85, v2
	v_mov_b32_e32 v86, v2
	v_mov_b32_e32 v87, v2
	v_mov_b32_e32 v88, v2
	v_mov_b32_e32 v89, v2
	v_mov_b32_e32 v98, v2
	v_mov_b32_e32 v99, v2
	v_mov_b32_e32 v100, v2
	v_mov_b32_e32 v101, v2
	v_mov_b32_e32 v102, v2
	v_mov_b32_e32 v103, v2
	v_mov_b32_e32 v104, v2
	v_mov_b32_e32 v105, v2
	v_mov_b32_e32 v114, v2
	v_mov_b32_e32 v115, v2
	v_mov_b32_e32 v116, v2
	v_mov_b32_e32 v117, v2
	v_mov_b32_e32 v118, v2
	v_mov_b32_e32 v119, v2
	v_mov_b32_e32 v120, v2
	v_mov_b32_e32 v121, v2
	v_mov_b32_e32 v74, v2
	v_mov_b32_e32 v75, v2
	v_mov_b32_e32 v76, v2
	v_mov_b32_e32 v77, v2
	v_mov_b32_e32 v78, v2
	v_mov_b32_e32 v79, v2
	v_mov_b32_e32 v80, v2
	v_mov_b32_e32 v81, v2
	v_mov_b32_e32 v90, v2
	v_mov_b32_e32 v91, v2
	v_mov_b32_e32 v92, v2
	v_mov_b32_e32 v93, v2
	v_mov_b32_e32 v94, v2
	v_mov_b32_e32 v95, v2
	v_mov_b32_e32 v96, v2
	v_mov_b32_e32 v97, v2
	v_mov_b32_e32 v106, v2
	v_mov_b32_e32 v107, v2
	v_mov_b32_e32 v108, v2
	v_mov_b32_e32 v109, v2
	v_mov_b32_e32 v110, v2
	v_mov_b32_e32 v111, v2
	v_mov_b32_e32 v112, v2
	v_mov_b32_e32 v113, v2
	v_mov_b32_e32 v122, v2
	v_mov_b32_e32 v123, v2
	v_mov_b32_e32 v124, v2
	v_mov_b32_e32 v125, v2
	v_mov_b32_e32 v126, v2
	v_mov_b32_e32 v127, v2
	v_mov_b32_e32 v128, v2
	v_mov_b32_e32 v129, v2
	.p2align	6

.LBB0_802:
	s_ashr_i32 s21, s20, 31
	s_lshl_b64 s[22:23], s[20:21], 19
	s_add_u32 s22, s49, s22
	s_addc_u32 s23, s52, s23
	s_and_b64 s[24:25], s[2:3], exec
	s_cselect_b32 s13, s23, s41
	s_cselect_b32 s21, s22, s40
	s_ashr_i32 s19, s18, 31
	s_lshl_b64 s[24:25], s[18:19], 19
	s_add_u32 s24, s53, s24
	s_addc_u32 s25, s55, s25
	s_and_b64 s[44:45], s[2:3], exec
	s_cselect_b32 s19, s25, s43
	s_cselect_b32 s64, s24, s42
	s_add_u32 s40, s40, 0x40080
	s_addc_u32 s41, s41, 0
	s_add_u32 s65, s42, 0x100
	v_mov_b32_e32 v2, 0
	s_addc_u32 s66, s43, 0
	s_mov_b32 s67, -2
	v_mov_b32_e32 v3, v2
	v_mov_b32_e32 v4, v2
	v_mov_b32_e32 v5, v2
	v_mov_b32_e32 v6, v2
	v_mov_b32_e32 v7, v2
	v_mov_b32_e32 v8, v2
	v_mov_b32_e32 v9, v2
	v_mov_b32_e32 v18, v2
	v_mov_b32_e32 v19, v2
	v_mov_b32_e32 v20, v2
	v_mov_b32_e32 v21, v2
	v_mov_b32_e32 v22, v2
	v_mov_b32_e32 v23, v2
	v_mov_b32_e32 v24, v2
	v_mov_b32_e32 v25, v2
	v_mov_b32_e32 v34, v2
	v_mov_b32_e32 v35, v2
	v_mov_b32_e32 v36, v2
	v_mov_b32_e32 v37, v2
	v_mov_b32_e32 v38, v2
	v_mov_b32_e32 v39, v2
	v_mov_b32_e32 v40, v2
	v_mov_b32_e32 v41, v2
	v_mov_b32_e32 v50, v2
	v_mov_b32_e32 v51, v2
	v_mov_b32_e32 v52, v2
	v_mov_b32_e32 v53, v2
	v_mov_b32_e32 v54, v2
	v_mov_b32_e32 v55, v2
	v_mov_b32_e32 v56, v2
	v_mov_b32_e32 v57, v2
	v_mov_b32_e32 v10, v2
	v_mov_b32_e32 v11, v2
	v_mov_b32_e32 v12, v2
	v_mov_b32_e32 v13, v2
	v_mov_b32_e32 v14, v2
	v_mov_b32_e32 v15, v2
	v_mov_b32_e32 v16, v2
	v_mov_b32_e32 v17, v2
	v_mov_b32_e32 v26, v2
	v_mov_b32_e32 v27, v2
	v_mov_b32_e32 v28, v2
	v_mov_b32_e32 v29, v2
	v_mov_b32_e32 v30, v2
	v_mov_b32_e32 v31, v2
	v_mov_b32_e32 v32, v2
	v_mov_b32_e32 v33, v2
	v_mov_b32_e32 v42, v2
	v_mov_b32_e32 v43, v2
	v_mov_b32_e32 v44, v2
	v_mov_b32_e32 v45, v2
	v_mov_b32_e32 v46, v2
	v_mov_b32_e32 v47, v2
	v_mov_b32_e32 v48, v2
	v_mov_b32_e32 v49, v2
	v_mov_b32_e32 v58, v2
	v_mov_b32_e32 v59, v2
	v_mov_b32_e32 v60, v2
	v_mov_b32_e32 v61, v2
	v_mov_b32_e32 v62, v2
	v_mov_b32_e32 v63, v2
	v_mov_b32_e32 v64, v2
	v_mov_b32_e32 v65, v2
	v_mov_b32_e32 v66, v2
	v_mov_b32_e32 v67, v2
	v_mov_b32_e32 v68, v2
	v_mov_b32_e32 v69, v2
	v_mov_b32_e32 v70, v2
	v_mov_b32_e32 v71, v2
	v_mov_b32_e32 v72, v2
	v_mov_b32_e32 v73, v2
	v_mov_b32_e32 v82, v2
	v_mov_b32_e32 v83, v2
	v_mov_b32_e32 v84, v2
	v_mov_b32_e32 v85, v2
	v_mov_b32_e32 v86, v2
	v_mov_b32_e32 v87, v2
	v_mov_b32_e32 v88, v2
	v_mov_b32_e32 v89, v2
	v_mov_b32_e32 v98, v2
	v_mov_b32_e32 v99, v2
	v_mov_b32_e32 v100, v2
	v_mov_b32_e32 v101, v2
	v_mov_b32_e32 v102, v2
	v_mov_b32_e32 v103, v2
	v_mov_b32_e32 v104, v2
	v_mov_b32_e32 v105, v2
	v_mov_b32_e32 v114, v2
	v_mov_b32_e32 v115, v2
	v_mov_b32_e32 v116, v2
	v_mov_b32_e32 v117, v2
	v_mov_b32_e32 v118, v2
	v_mov_b32_e32 v119, v2
	v_mov_b32_e32 v120, v2
	v_mov_b32_e32 v121, v2
	v_mov_b32_e32 v74, v2
	v_mov_b32_e32 v75, v2
	v_mov_b32_e32 v76, v2
	v_mov_b32_e32 v77, v2
	v_mov_b32_e32 v78, v2
	v_mov_b32_e32 v79, v2
	v_mov_b32_e32 v80, v2
	v_mov_b32_e32 v81, v2
	v_mov_b32_e32 v90, v2
	v_mov_b32_e32 v91, v2
	v_mov_b32_e32 v92, v2
	v_mov_b32_e32 v93, v2
	v_mov_b32_e32 v94, v2
	v_mov_b32_e32 v95, v2
	v_mov_b32_e32 v96, v2
	v_mov_b32_e32 v97, v2
	v_mov_b32_e32 v106, v2
	v_mov_b32_e32 v107, v2
	v_mov_b32_e32 v108, v2
	v_mov_b32_e32 v109, v2
	v_mov_b32_e32 v110, v2
	v_mov_b32_e32 v111, v2
	v_mov_b32_e32 v112, v2
	v_mov_b32_e32 v113, v2
	v_mov_b32_e32 v122, v2
	v_mov_b32_e32 v123, v2
	v_mov_b32_e32 v124, v2
	v_mov_b32_e32 v125, v2
	v_mov_b32_e32 v126, v2
	v_mov_b32_e32 v127, v2
	v_mov_b32_e32 v128, v2
	v_mov_b32_e32 v129, v2
	.p2align	6

.LBB0_889:
	s_ashr_i32 s21, s20, 31
	s_lshl_b64 s[22:23], s[20:21], 20
	s_add_u32 s22, s35, s22
	s_addc_u32 s23, s48, s23
	s_and_b64 s[24:25], s[2:3], exec
	s_cselect_b32 s13, s23, s41
	s_cselect_b32 s21, s22, s40
	s_ashr_i32 s19, s18, 31
	s_lshl_b64 s[24:25], s[18:19], 20
	s_add_u32 s24, s49, s24
	s_addc_u32 s25, s52, s25
	s_and_b64 s[44:45], s[2:3], exec
	s_cselect_b32 s19, s25, s43
	s_cselect_b32 s74, s24, s42
	s_add_u32 s40, s40, 0x80080
	s_addc_u32 s41, s41, 0
	s_add_u32 s75, s42, 0x100
	v_mov_b32_e32 v2, 0
	s_addc_u32 s81, s43, 0
	s_mov_b32 s82, -2
	v_mov_b32_e32 v3, v2
	v_mov_b32_e32 v4, v2
	v_mov_b32_e32 v5, v2
	v_mov_b32_e32 v6, v2
	v_mov_b32_e32 v7, v2
	v_mov_b32_e32 v8, v2
	v_mov_b32_e32 v9, v2
	v_mov_b32_e32 v10, v2
	v_mov_b32_e32 v11, v2
	v_mov_b32_e32 v12, v2
	v_mov_b32_e32 v13, v2
	v_mov_b32_e32 v14, v2
	v_mov_b32_e32 v15, v2
	v_mov_b32_e32 v16, v2
	v_mov_b32_e32 v17, v2
	v_mov_b32_e32 v34, v2
	v_mov_b32_e32 v35, v2
	v_mov_b32_e32 v36, v2
	v_mov_b32_e32 v37, v2
	v_mov_b32_e32 v38, v2
	v_mov_b32_e32 v39, v2
	v_mov_b32_e32 v40, v2
	v_mov_b32_e32 v41, v2
	v_mov_b32_e32 v42, v2
	v_mov_b32_e32 v43, v2
	v_mov_b32_e32 v44, v2
	v_mov_b32_e32 v45, v2
	v_mov_b32_e32 v46, v2
	v_mov_b32_e32 v47, v2
	v_mov_b32_e32 v48, v2
	v_mov_b32_e32 v49, v2
	v_mov_b32_e32 v18, v2
	v_mov_b32_e32 v19, v2
	v_mov_b32_e32 v20, v2
	v_mov_b32_e32 v21, v2
	v_mov_b32_e32 v22, v2
	v_mov_b32_e32 v23, v2
	v_mov_b32_e32 v24, v2
	v_mov_b32_e32 v25, v2
	v_mov_b32_e32 v26, v2
	v_mov_b32_e32 v27, v2
	v_mov_b32_e32 v28, v2
	v_mov_b32_e32 v29, v2
	v_mov_b32_e32 v30, v2
	v_mov_b32_e32 v31, v2
	v_mov_b32_e32 v32, v2
	v_mov_b32_e32 v33, v2
	v_mov_b32_e32 v50, v2
	v_mov_b32_e32 v51, v2
	v_mov_b32_e32 v52, v2
	v_mov_b32_e32 v53, v2
	v_mov_b32_e32 v54, v2
	v_mov_b32_e32 v55, v2
	v_mov_b32_e32 v56, v2
	v_mov_b32_e32 v57, v2
	v_mov_b32_e32 v58, v2
	v_mov_b32_e32 v59, v2
	v_mov_b32_e32 v60, v2
	v_mov_b32_e32 v61, v2
	v_mov_b32_e32 v62, v2
	v_mov_b32_e32 v63, v2
	v_mov_b32_e32 v64, v2
	v_mov_b32_e32 v65, v2
	v_mov_b32_e32 v66, v2
	v_mov_b32_e32 v67, v2
	v_mov_b32_e32 v68, v2
	v_mov_b32_e32 v69, v2
	v_mov_b32_e32 v70, v2
	v_mov_b32_e32 v71, v2
	v_mov_b32_e32 v72, v2
	v_mov_b32_e32 v73, v2
	v_mov_b32_e32 v74, v2
	v_mov_b32_e32 v75, v2
	v_mov_b32_e32 v76, v2
	v_mov_b32_e32 v77, v2
	v_mov_b32_e32 v78, v2
	v_mov_b32_e32 v79, v2
	v_mov_b32_e32 v80, v2
	v_mov_b32_e32 v81, v2
	v_mov_b32_e32 v98, v2
	v_mov_b32_e32 v99, v2
	v_mov_b32_e32 v100, v2
	v_mov_b32_e32 v101, v2
	v_mov_b32_e32 v102, v2
	v_mov_b32_e32 v103, v2
	v_mov_b32_e32 v104, v2
	v_mov_b32_e32 v105, v2
	v_mov_b32_e32 v106, v2
	v_mov_b32_e32 v107, v2
	v_mov_b32_e32 v108, v2
	v_mov_b32_e32 v109, v2
	v_mov_b32_e32 v110, v2
	v_mov_b32_e32 v111, v2
	v_mov_b32_e32 v112, v2
	v_mov_b32_e32 v113, v2
	v_mov_b32_e32 v82, v2
	v_mov_b32_e32 v83, v2
	v_mov_b32_e32 v84, v2
	v_mov_b32_e32 v85, v2
	v_mov_b32_e32 v86, v2
	v_mov_b32_e32 v87, v2
	v_mov_b32_e32 v88, v2
	v_mov_b32_e32 v89, v2
	v_mov_b32_e32 v90, v2
	v_mov_b32_e32 v91, v2
	v_mov_b32_e32 v92, v2
	v_mov_b32_e32 v93, v2
	v_mov_b32_e32 v94, v2
	v_mov_b32_e32 v95, v2
	v_mov_b32_e32 v96, v2
	v_mov_b32_e32 v97, v2
	v_mov_b32_e32 v118, v2
	v_mov_b32_e32 v119, v2
	v_mov_b32_e32 v120, v2
	v_mov_b32_e32 v121, v2
	v_mov_b32_e32 v114, v2
	v_mov_b32_e32 v115, v2
	v_mov_b32_e32 v116, v2
	v_mov_b32_e32 v117, v2
	v_mov_b32_e32 v126, v2
	v_mov_b32_e32 v127, v2
	v_mov_b32_e32 v128, v2
	v_mov_b32_e32 v129, v2
	v_mov_b32_e32 v122, v2
	v_mov_b32_e32 v123, v2
	v_mov_b32_e32 v124, v2
	v_mov_b32_e32 v125, v2
	.p2align	6

.LBB0_1042:
	s_ashr_i32 s19, s18, 31
	s_lshl_b64 s[20:21], s[18:19], 20
	s_add_u32 s20, s35, s20
	s_addc_u32 s21, s42, s21
	s_and_b64 s[22:23], s[2:3], exec
	s_cselect_b32 s13, s21, s37
	s_cselect_b32 s19, s20, s36
	s_ashr_i32 s17, s16, 31
	s_lshl_b64 s[22:23], s[16:17], 20
	s_add_u32 s22, s43, s22
	s_addc_u32 s23, s44, s23
	s_and_b64 s[40:41], s[2:3], exec
	s_cselect_b32 s17, s23, s39
	s_cselect_b32 s60, s22, s38
	s_add_u32 s36, s36, 0x80080
	s_addc_u32 s37, s37, 0
	s_add_u32 s61, s38, 0x100
	v_mov_b32_e32 v2, 0
	s_addc_u32 s62, s39, 0
	s_mov_b32 s63, -2
	v_mov_b32_e32 v3, v2
	v_mov_b32_e32 v4, v2
	v_mov_b32_e32 v5, v2
	v_mov_b32_e32 v6, v2
	v_mov_b32_e32 v7, v2
	v_mov_b32_e32 v8, v2
	v_mov_b32_e32 v9, v2
	v_mov_b32_e32 v18, v2
	v_mov_b32_e32 v19, v2
	v_mov_b32_e32 v20, v2
	v_mov_b32_e32 v21, v2
	v_mov_b32_e32 v22, v2
	v_mov_b32_e32 v23, v2
	v_mov_b32_e32 v24, v2
	v_mov_b32_e32 v25, v2
	v_mov_b32_e32 v34, v2
	v_mov_b32_e32 v35, v2
	v_mov_b32_e32 v36, v2
	v_mov_b32_e32 v37, v2
	v_mov_b32_e32 v38, v2
	v_mov_b32_e32 v39, v2
	v_mov_b32_e32 v40, v2
	v_mov_b32_e32 v41, v2
	v_mov_b32_e32 v50, v2
	v_mov_b32_e32 v51, v2
	v_mov_b32_e32 v52, v2
	v_mov_b32_e32 v53, v2
	v_mov_b32_e32 v54, v2
	v_mov_b32_e32 v55, v2
	v_mov_b32_e32 v56, v2
	v_mov_b32_e32 v57, v2
	v_mov_b32_e32 v10, v2
	v_mov_b32_e32 v11, v2
	v_mov_b32_e32 v12, v2
	v_mov_b32_e32 v13, v2
	v_mov_b32_e32 v14, v2
	v_mov_b32_e32 v15, v2
	v_mov_b32_e32 v16, v2
	v_mov_b32_e32 v17, v2
	v_mov_b32_e32 v26, v2
	v_mov_b32_e32 v27, v2
	v_mov_b32_e32 v28, v2
	v_mov_b32_e32 v29, v2
	v_mov_b32_e32 v30, v2
	v_mov_b32_e32 v31, v2
	v_mov_b32_e32 v32, v2
	v_mov_b32_e32 v33, v2
	v_mov_b32_e32 v42, v2
	v_mov_b32_e32 v43, v2
	v_mov_b32_e32 v44, v2
	v_mov_b32_e32 v45, v2
	v_mov_b32_e32 v46, v2
	v_mov_b32_e32 v47, v2
	v_mov_b32_e32 v48, v2
	v_mov_b32_e32 v49, v2
	v_mov_b32_e32 v58, v2
	v_mov_b32_e32 v59, v2
	v_mov_b32_e32 v60, v2
	v_mov_b32_e32 v61, v2
	v_mov_b32_e32 v62, v2
	v_mov_b32_e32 v63, v2
	v_mov_b32_e32 v64, v2
	v_mov_b32_e32 v65, v2
	v_mov_b32_e32 v66, v2
	v_mov_b32_e32 v67, v2
	v_mov_b32_e32 v68, v2
	v_mov_b32_e32 v69, v2
	v_mov_b32_e32 v70, v2
	v_mov_b32_e32 v71, v2
	v_mov_b32_e32 v72, v2
	v_mov_b32_e32 v73, v2
	v_mov_b32_e32 v82, v2
	v_mov_b32_e32 v83, v2
	v_mov_b32_e32 v84, v2
	v_mov_b32_e32 v85, v2
	v_mov_b32_e32 v86, v2
	v_mov_b32_e32 v87, v2
	v_mov_b32_e32 v88, v2
	v_mov_b32_e32 v89, v2
	v_mov_b32_e32 v98, v2
	v_mov_b32_e32 v99, v2
	v_mov_b32_e32 v100, v2
	v_mov_b32_e32 v101, v2
	v_mov_b32_e32 v102, v2
	v_mov_b32_e32 v103, v2
	v_mov_b32_e32 v104, v2
	v_mov_b32_e32 v105, v2
	v_mov_b32_e32 v114, v2
	v_mov_b32_e32 v115, v2
	v_mov_b32_e32 v116, v2
	v_mov_b32_e32 v117, v2
	v_mov_b32_e32 v118, v2
	v_mov_b32_e32 v119, v2
	v_mov_b32_e32 v120, v2
	v_mov_b32_e32 v121, v2
	v_mov_b32_e32 v74, v2
	v_mov_b32_e32 v75, v2
	v_mov_b32_e32 v76, v2
	v_mov_b32_e32 v77, v2
	v_mov_b32_e32 v78, v2
	v_mov_b32_e32 v79, v2
	v_mov_b32_e32 v80, v2
	v_mov_b32_e32 v81, v2
	v_mov_b32_e32 v90, v2
	v_mov_b32_e32 v91, v2
	v_mov_b32_e32 v92, v2
	v_mov_b32_e32 v93, v2
	v_mov_b32_e32 v94, v2
	v_mov_b32_e32 v95, v2
	v_mov_b32_e32 v96, v2
	v_mov_b32_e32 v97, v2
	v_mov_b32_e32 v106, v2
	v_mov_b32_e32 v107, v2
	v_mov_b32_e32 v108, v2
	v_mov_b32_e32 v109, v2
	v_mov_b32_e32 v110, v2
	v_mov_b32_e32 v111, v2
	v_mov_b32_e32 v112, v2
	v_mov_b32_e32 v113, v2
	v_mov_b32_e32 v122, v2
	v_mov_b32_e32 v123, v2
	v_mov_b32_e32 v124, v2
	v_mov_b32_e32 v125, v2
	v_mov_b32_e32 v126, v2
	v_mov_b32_e32 v127, v2
	v_mov_b32_e32 v128, v2
	v_mov_b32_e32 v129, v2
	.p2align	6

.LBB0_1137:
	s_add_u32 s67, s24, 0x100
	v_mov_b32_e32 v2, 0
	s_addc_u32 s69, s25, 0
	s_mov_b32 s74, -2
	v_mov_b32_e32 v3, v2
	v_mov_b32_e32 v4, v2
	v_mov_b32_e32 v5, v2
	v_mov_b32_e32 v6, v2
	v_mov_b32_e32 v7, v2
	v_mov_b32_e32 v8, v2
	v_mov_b32_e32 v9, v2
	v_mov_b32_e32 v10, v2
	v_mov_b32_e32 v11, v2
	v_mov_b32_e32 v12, v2
	v_mov_b32_e32 v13, v2
	v_mov_b32_e32 v14, v2
	v_mov_b32_e32 v15, v2
	v_mov_b32_e32 v16, v2
	v_mov_b32_e32 v17, v2
	v_mov_b32_e32 v34, v2
	v_mov_b32_e32 v35, v2
	v_mov_b32_e32 v36, v2
	v_mov_b32_e32 v37, v2
	v_mov_b32_e32 v38, v2
	v_mov_b32_e32 v39, v2
	v_mov_b32_e32 v40, v2
	v_mov_b32_e32 v41, v2
	v_mov_b32_e32 v42, v2
	v_mov_b32_e32 v43, v2
	v_mov_b32_e32 v44, v2
	v_mov_b32_e32 v45, v2
	v_mov_b32_e32 v46, v2
	v_mov_b32_e32 v47, v2
	v_mov_b32_e32 v48, v2
	v_mov_b32_e32 v49, v2
	v_mov_b32_e32 v18, v2
	v_mov_b32_e32 v19, v2
	v_mov_b32_e32 v20, v2
	v_mov_b32_e32 v21, v2
	v_mov_b32_e32 v22, v2
	v_mov_b32_e32 v23, v2
	v_mov_b32_e32 v24, v2
	v_mov_b32_e32 v25, v2
	v_mov_b32_e32 v26, v2
	v_mov_b32_e32 v27, v2
	v_mov_b32_e32 v28, v2
	v_mov_b32_e32 v29, v2
	v_mov_b32_e32 v30, v2
	v_mov_b32_e32 v31, v2
	v_mov_b32_e32 v32, v2
	v_mov_b32_e32 v33, v2
	v_mov_b32_e32 v50, v2
	v_mov_b32_e32 v51, v2
	v_mov_b32_e32 v52, v2
	v_mov_b32_e32 v53, v2
	v_mov_b32_e32 v54, v2
	v_mov_b32_e32 v55, v2
	v_mov_b32_e32 v56, v2
	v_mov_b32_e32 v57, v2
	v_mov_b32_e32 v58, v2
	v_mov_b32_e32 v59, v2
	v_mov_b32_e32 v60, v2
	v_mov_b32_e32 v61, v2
	v_mov_b32_e32 v62, v2
	v_mov_b32_e32 v63, v2
	v_mov_b32_e32 v64, v2
	v_mov_b32_e32 v65, v2
	v_mov_b32_e32 v66, v2
	v_mov_b32_e32 v67, v2
	v_mov_b32_e32 v68, v2
	v_mov_b32_e32 v69, v2
	v_mov_b32_e32 v70, v2
	v_mov_b32_e32 v71, v2
	v_mov_b32_e32 v72, v2
	v_mov_b32_e32 v73, v2
	v_mov_b32_e32 v74, v2
	v_mov_b32_e32 v75, v2
	v_mov_b32_e32 v76, v2
	v_mov_b32_e32 v77, v2
	v_mov_b32_e32 v78, v2
	v_mov_b32_e32 v79, v2
	v_mov_b32_e32 v80, v2
	v_mov_b32_e32 v81, v2
	v_mov_b32_e32 v98, v2
	v_mov_b32_e32 v99, v2
	v_mov_b32_e32 v100, v2
	v_mov_b32_e32 v101, v2
	v_mov_b32_e32 v102, v2
	v_mov_b32_e32 v103, v2
	v_mov_b32_e32 v104, v2
	v_mov_b32_e32 v105, v2
	v_mov_b32_e32 v106, v2
	v_mov_b32_e32 v107, v2
	v_mov_b32_e32 v108, v2
	v_mov_b32_e32 v109, v2
	v_mov_b32_e32 v110, v2
	v_mov_b32_e32 v111, v2
	v_mov_b32_e32 v112, v2
	v_mov_b32_e32 v113, v2
	v_mov_b32_e32 v82, v2
	v_mov_b32_e32 v83, v2
	v_mov_b32_e32 v84, v2
	v_mov_b32_e32 v85, v2
	v_mov_b32_e32 v86, v2
	v_mov_b32_e32 v87, v2
	v_mov_b32_e32 v88, v2
	v_mov_b32_e32 v89, v2
	v_mov_b32_e32 v90, v2
	v_mov_b32_e32 v91, v2
	v_mov_b32_e32 v92, v2
	v_mov_b32_e32 v93, v2
	v_mov_b32_e32 v94, v2
	v_mov_b32_e32 v95, v2
	v_mov_b32_e32 v96, v2
	v_mov_b32_e32 v97, v2
	v_mov_b32_e32 v118, v2
	v_mov_b32_e32 v119, v2
	v_mov_b32_e32 v120, v2
	v_mov_b32_e32 v121, v2
	v_mov_b32_e32 v114, v2
	v_mov_b32_e32 v115, v2
	v_mov_b32_e32 v116, v2
	v_mov_b32_e32 v117, v2
	v_mov_b32_e32 v126, v2
	v_mov_b32_e32 v127, v2
	v_mov_b32_e32 v128, v2
	v_mov_b32_e32 v129, v2
	v_mov_b32_e32 v122, v2
	v_mov_b32_e32 v123, v2
	v_mov_b32_e32 v124, v2
	v_mov_b32_e32 v125, v2
	.p2align	6
